# grid barrier and EpiNorm exchange: acquire invalidate issued before the spin (off the release path); scan first record by LDS-DMA
# speedup vs baseline: 1.0425x; 1.0141x over previous
.LBB0_54:
	s_or_b64 exec, exec, s[8:9]
	v_cvt_f32_u32_e32 v4, v2
	s_waitcnt vmcnt(0)
	v_readfirstlane_b32 s0, v3
	v_sub_u32_e32 v3, 0, v2
	v_rcp_iflag_f32_e32 v4, v4
	v_add_u32_e32 v5, s0, v1
	v_mul_f32_e32 v4, 0x4f7ffffe, v4
	v_cvt_u32_f32_e32 v4, v4
	v_mul_lo_u32 v1, v3, v4
	v_mul_hi_u32 v1, v4, v1
	v_add_u32_e32 v1, v4, v1
	v_mul_hi_u32 v1, v5, v1
	v_mul_lo_u32 v3, v1, v2
	v_sub_u32_e32 v3, v5, v3
	v_add_u32_e32 v4, 1, v1
	v_cmp_ge_u32_e32 vcc, v3, v2
	s_nop 1
	v_cndmask_b32_e32 v1, v1, v4, vcc
	v_sub_u32_e32 v4, v3, v2
	v_cndmask_b32_e32 v3, v3, v4, vcc
	v_add_u32_e32 v4, 1, v1
	v_cmp_ge_u32_e32 vcc, v3, v2
	v_add_u32_e32 v3, 1, v5
	s_nop 0
	v_cndmask_b32_e32 v1, v1, v4, vcc
	v_mul_lo_u32 v4, v2, v1
	v_add_u32_e32 v2, v4, v2
	v_cmp_ne_u32_e32 vcc, v3, v2
	s_and_saveexec_b64 s[0:1], vcc
	s_xor_b64 s[8:9], exec, s[0:1]
	s_cbranch_execz .LBB0_68
	v_readlane_b32 s0, v255, 16
	v_readlane_b32 s1, v255, 17
	s_waitcnt lgkmcnt(0)
	s_nop 3
	buffer_inv sc1
	global_load_dword v0, v197, s[0:1] sc1
	s_waitcnt vmcnt(0)
	v_cmp_eq_u32_e32 vcc, v0, v1
	s_and_saveexec_b64 s[12:13], vcc
	s_cbranch_execz .LBB0_67
	s_mov_b32 s0, 1
	s_mov_b64 s[14:15], 0
	s_branch .LBB0_58

.LBB0_67:
	s_or_b64 exec, exec, s[12:13]
	s_waitcnt vmcnt(0)
	s_waitcnt vmcnt(0)

.LBB0_374:
	s_lshl_b32 s78, s26, 5
	s_mul_i32 s4, s26, 0x1e8000
	s_mul_hi_i32 s13, s78, 0xf400
	s_add_u32 s12, s3, s4
	s_addc_u32 s13, s19, s13
	v_readfirstlane_b32 s4, v212
	v_and_b32_e32 v0, 63, v212
	s_lshr_b32 s4, s4, 6
	s_lshl_b32 s27, s4, 10
	v_lshl_add_u32 v0, v0, 4, s27
	s_mov_b32 s28, s4
.Lscan_r0_loop:
	s_lshl_b32 s29, s28, 10
	s_mov_b32 m0, s29
	s_nop 0
	global_load_lds_dwordx4 v0, s[12:13]
	v_add_u32_e32 v0, 0x2000, v0
	s_add_i32 s28, s28, 8
	s_cmp_lt_u32 s28, 61
	s_cbranch_scc1 .Lscan_r0_loop
	s_waitcnt vmcnt(0)

.LBB0_729:
	s_or_b64 exec, exec, s[12:13]
	s_cmp_gt_u32 s1, 63
	s_cbranch_scc1 .LBB0_735
	s_lshl_b32 s8, s8, 6
	s_ashr_i32 s9, s8, 31
	s_lshl_b64 s[8:9], s[8:9], 2
	s_add_u32 s8, s2, s8
	s_addc_u32 s9, s4, s9
	v_mov_b32_e32 v131, 0x3fffff
	buffer_inv sc1
	s_branch .LBB0_732

.LBB0_734:
.LBB0_735:
	s_waitcnt vmcnt(0) lgkmcnt(0)
	s_barrier
	s_and_saveexec_b64 s[8:9], s[38:39]
	s_cbranch_execz .LBB0_737
	v_lshl_add_u64 v[128:129], v[128:129], 4, s[14:15]
	global_load_dword v131, v[128:129], off sc1
	global_load_dword v132, v[128:129], off offset:4 sc1
	s_waitcnt vmcnt(1)
	v_add_f32_e32 v131, 0, v131
	s_waitcnt vmcnt(0)
	v_add_f32_e32 v131, v131, v132
	global_load_dword v132, v[128:129], off offset:8 sc1
	s_waitcnt vmcnt(0)
	v_add_f32_e32 v131, v131, v132
	global_load_dword v128, v[128:129], off offset:12 sc1
	s_waitcnt vmcnt(0)
	v_add_f32_e32 v128, v131, v128
	v_fmamk_f32 v128, v128, 0x3a800000, v224
	v_cmp_gt_f32_e32 vcc, s85, v128
	v_mul_f32_e32 v129, 0x4b800000, v128
	s_nop 0
	v_cndmask_b32_e32 v128, v128, v129, vcc
	v_rsq_f32_e32 v128, v128
	s_nop 0
	v_mul_f32_e32 v129, 0x45800000, v128
	v_cndmask_b32_e32 v128, v128, v129, vcc
	v_lshl_add_u32 v129, v130, 2, 0
	ds_write_b32 v129, v128 offset:8192

.LBB0_1007:
	s_or_b64 exec, exec, s[8:9]
	s_cmp_gt_u32 s58, 63
	s_cbranch_scc1 .LBB0_1013
	s_lshl_b32 s2, s18, 6
	s_ashr_i32 s3, s2, 31
	s_lshl_b64 s[2:3], s[2:3], 2
	s_add_u32 s8, s0, s2
	s_addc_u32 s9, s1, s3
	v_mov_b32_e32 v3, 0x3fffff
	buffer_inv sc1
	s_branch .LBB0_1010

.LBB0_1012:
.LBB0_1013:
	s_waitcnt vmcnt(0) lgkmcnt(0)
	s_barrier
	s_and_saveexec_b64 s[8:9], s[38:39]
	s_cbranch_execz .LBB0_1015
	v_lshl_add_u64 v[0:1], v[0:1], 4, s[6:7]
	global_load_dword v3, v[0:1], off sc1
	global_load_dword v4, v[0:1], off offset:4 sc1
	s_waitcnt vmcnt(1)
	v_add_f32_e32 v3, 0, v3
	s_waitcnt vmcnt(0)
	v_add_f32_e32 v3, v3, v4
	global_load_dword v4, v[0:1], off offset:8 sc1
	s_waitcnt vmcnt(0)
	v_add_f32_e32 v3, v3, v4
	global_load_dword v0, v[0:1], off offset:12 sc1
	s_waitcnt vmcnt(0)
	v_add_f32_e32 v0, v3, v0
	v_fmamk_f32 v0, v0, 0x3a800000, v224
	v_cmp_gt_f32_e32 vcc, s85, v0
	v_mul_f32_e32 v1, 0x4b800000, v0
	s_nop 0
	v_cndmask_b32_e32 v0, v0, v1, vcc
	v_rsq_f32_e32 v0, v0
	s_nop 0
	v_mul_f32_e32 v1, 0x45800000, v0
	v_cndmask_b32_e32 v0, v0, v1, vcc
	v_lshl_add_u32 v1, v2, 2, 0
	ds_write_b32 v1, v0 offset:8192

.LBB0_1062:
	s_or_b64 exec, exec, s[8:9]
	s_cmp_gt_u32 s0, 63
	s_cbranch_scc1 .LBB0_1068
	s_lshl_b32 s6, s6, 6
	s_ashr_i32 s7, s6, 31
	s_lshl_b64 s[6:7], s[6:7], 2
	s_add_u32 s6, s1, s6
	s_addc_u32 s7, s3, s7
	v_mov_b32_e32 v131, 0x3fffff
	buffer_inv sc1
	s_branch .LBB0_1065

.LBB0_1067:
.LBB0_1068:
	s_waitcnt vmcnt(0) lgkmcnt(0)
	s_barrier
	s_and_saveexec_b64 s[6:7], s[38:39]
	s_cbranch_execz .LBB0_1070
	v_lshl_add_u64 v[128:129], v[128:129], 4, s[12:13]
	global_load_dword v131, v[128:129], off sc1
	global_load_dword v132, v[128:129], off offset:4 sc1
	s_waitcnt vmcnt(1)
	v_add_f32_e32 v131, 0, v131
	s_waitcnt vmcnt(0)
	v_add_f32_e32 v131, v131, v132
	global_load_dword v132, v[128:129], off offset:8 sc1
	s_waitcnt vmcnt(0)
	v_add_f32_e32 v131, v131, v132
	global_load_dword v128, v[128:129], off offset:12 sc1
	s_waitcnt vmcnt(0)
	v_add_f32_e32 v128, v131, v128
	v_fmamk_f32 v128, v128, 0x3a800000, v224
	v_cmp_gt_f32_e32 vcc, s85, v128
	v_mul_f32_e32 v129, 0x4b800000, v128
	s_nop 0
	v_cndmask_b32_e32 v128, v128, v129, vcc
	v_rsq_f32_e32 v128, v128
	s_nop 0
	v_mul_f32_e32 v129, 0x45800000, v128
	v_cndmask_b32_e32 v128, v128, v129, vcc
	v_lshl_add_u32 v129, v130, 2, 0
	ds_write_b32 v129, v128 offset:8192
